# PEER combine: the three dependent scale-table gathers issued together with the first one (two fewer load round trips per token), on top of previous fixes
# baseline (speedup 1.0000x reference)
.LBB0_1138:
	s_or_b64 exec, exec, s[14:15]
	v_add_co_u32_e32 v14, vcc, 0x10000, v14
	v_bfi_b32 v21, s24, v22, v21
	s_nop 0
	v_addc_co_u32_e32 v15, vcc, 0, v15, vcc
	v_mov_b32_e32 v25, v46
	v_bfi_b32 v22, s24, v24, v23
	v_mul_f32_e32 v20, 0.5, v20
	v_mul_f32_e32 v17, 0.5, v17
	v_add_f32_e32 v21, 1.0, v21
	v_add_f32_e32 v22, 1.0, v22
	v_mul_f32_e32 v20, v20, v21
	v_mul_f32_e32 v17, v17, v22
	v_readlane_b32 s28, v250, 0
	v_add_u32_e32 v2, s76, v2
	v_mul_f32_e32 v12, v12, v20
	v_mul_f32_e32 v13, v13, v17
	v_readlane_b32 s30, v250, 2
	v_readlane_b32 s31, v250, 3
	v_cmp_lt_i32_e32 vcc, s25, v2
	s_waitcnt vmcnt(1)
	v_mul_f32_e32 v12, v16, v12
	v_lshl_add_u64 v[14:15], s[30:31], 0, v[6:7]
	v_lshl_add_u64 v[4:5], v[4:5], 0, s[10:11]
	v_lshl_add_u64 v[6:7], v[6:7], 0, s[10:11]
	v_lshl_add_u64 v[8:9], v[8:9], 0, s[12:13]
	s_or_b64 s[0:1], vcc, s[0:1]
	v_lshl_add_u64 v[10:11], v[10:11], 0, s[12:13]
	v_readlane_b32 s29, v250, 1
	s_waitcnt vmcnt(0)
	v_mul_f32_e32 v13, v25, v13
	v_cvt_pk_f16_f32 v12, v12, v13
	global_store_dword v[14:15], v12, off
	s_andn2_b64 exec, exec, s[0:1]
	s_cbranch_execz .LBB0_1147
.LBB0_1139:
	v_lshl_add_u64 v[12:13], s[30:31], 0, v[8:9]
	v_add_co_u32_e32 v12, vcc, 0x2ade6000, v12
	v_lshl_add_u64 v[16:17], s[30:31], 0, v[10:11]
	s_nop 0
	v_addc_co_u32_e32 v13, vcc, 0, v13, vcc
	global_load_dwordx2 v[14:15], v[12:13], off
	v_lshl_add_u64 v[12:13], s[30:31], 0, v[4:5]
	v_add_co_u32_e32 v20, vcc, 0x40d86000, v12
	s_nop 1
	v_addc_co_u32_e32 v21, vcc, 0, v13, vcc
	v_add_co_u32_e32 v22, vcc, 0x41206000, v12
	s_nop 1
	v_addc_co_u32_e32 v23, vcc, 0, v13, vcc
	v_add_co_u32_e32 v26, vcc, 0x41686000, v12
	s_nop 1
	v_addc_co_u32_e32 v27, vcc, 0, v13, vcc
	v_add_co_u32_e32 v28, vcc, 0x41b06000, v12
	s_nop 1
	v_addc_co_u32_e32 v29, vcc, 0, v13, vcc
	v_add_co_u32_e32 v32, vcc, 0x41f86000, v12
	global_load_dword v24, v[22:23], off
	s_nop 0
	global_load_dword v23, v[28:29], off
	v_addc_co_u32_e32 v33, vcc, 0, v13, vcc
	v_add_co_u32_e32 v34, vcc, 0x42406000, v12
	s_waitcnt vmcnt(0)
	v_cvt_f32_f16_e32 v31, v23
	v_addc_co_u32_e32 v35, vcc, 0, v13, vcc
	v_add_co_u32_e32 v36, vcc, 0x42886000, v12
	s_nop 1
	v_addc_co_u32_e32 v37, vcc, 0, v13, vcc
	global_load_dword v30, v[20:21], off
	global_load_dword v29, v[26:27], off
	s_nop 0
	global_load_dword v26, v[32:33], off
	global_load_dword v25, v[36:37], off
	v_add_co_u32_e32 v12, vcc, 0x42d06000, v12
	s_waitcnt vmcnt(2)
	v_cvt_f32_f16_e32 v22, v29
	v_addc_co_u32_e32 v13, vcc, 0, v13, vcc
	global_load_dword v28, v[34:35], off
	global_load_dword v27, v[12:13], off
	v_add_co_u32_e32 v20, vcc, 0x2b6e6000, v16
	v_ashrrev_i32_e32 v13, 31, v14
	s_nop 0
	v_addc_co_u32_e32 v21, vcc, 0, v17, vcc
	v_mov_b32_e32 v12, v14
	v_lshl_add_u64 v[16:17], v[12:13], 2, s[8:9]
	global_load_dwordx2 v[12:13], v[20:21], off
	global_load_dword v14, v[16:17], off
	s_mov_b64 s[98:99], 0x10000
	v_ashrrev_i32_e32 v41, 31, v15
	v_mov_b32_e32 v40, v15
	v_lshl_add_u64 v[40:41], v[40:41], 2, s[8:9]
	global_load_dword v44, v[40:41], off
	v_lshl_add_u64 v[42:43], v[16:17], 0, s[98:99]
	global_load_dword v45, v[42:43], off
	v_lshl_add_u64 v[42:43], v[40:41], 0, s[98:99]
	global_load_dword v46, v[42:43], off
	v_cvt_f32_f16_e32 v20, v30
	v_cvt_f32_f16_e32 v21, v24
	v_add_f32_e32 v20, 0, v20
	v_add_f32_e32 v20, v20, v21
	s_waitcnt vmcnt(5)
	v_cvt_f32_f16_e32 v21, v26
	v_add_f32_e32 v20, v20, v22
	v_add_f32_e32 v20, v20, v31
	s_waitcnt vmcnt(4)
	v_cvt_f32_f16_e32 v31, v25
	v_add_f32_e32 v20, v20, v21
	s_waitcnt vmcnt(3)
	v_cvt_f32_f16_e32 v22, v28
	s_waitcnt vmcnt(2)
	v_cvt_f32_f16_e32 v32, v27
	v_add_f32_e32 v20, v20, v22
	v_add_f32_e32 v20, v20, v31
	v_add_f32_e32 v20, v20, v32
	s_waitcnt vmcnt(0)
	v_mul_f32_e32 v20, v20, v14
	v_mul_f32_e32 v21, 0x3f3504f3, v20
	v_cmp_nlt_f32_e64 s[14:15], |v21|, 1.0
	s_and_saveexec_b64 s[26:27], s[14:15]
	s_xor_b64 s[14:15], exec, s[26:27]
	s_cbranch_execz .LBB0_1141
	v_fma_f32 v14, |v21|, s2, v18
	v_fma_f32 v14, |v21|, v14, s16
	v_fma_f32 v14, |v21|, v14, s17
	v_fma_f32 v14, |v21|, v14, s18
	v_fma_f32 v14, |v21|, v14, s19
	v_fma_f32 v14, |v21|, v14, s20
	v_fma_f32 v14, |v21|, v14, |v21|
	v_mul_f32_e32 v22, 0xbfb8aa3b, v14
	v_fma_f32 v31, v14, s21, -v22
	v_rndne_f32_e32 v32, v22
	v_fmac_f32_e32 v31, 0xb2a5705f, v14
	v_sub_f32_e32 v22, v22, v32
	v_add_f32_e32 v22, v22, v31
	v_cvt_i32_f32_e32 v31, v32
	v_exp_f32_e32 v22, v22
	v_cmp_nlt_f32_e32 vcc, s22, v14
	v_ldexp_f32 v22, v22, v31
	s_nop 0
	v_cndmask_b32_e32 v22, 0, v22, vcc
	v_cmp_ngt_f32_e32 vcc, s23, v14
	s_nop 1
	v_cndmask_b32_e32 v14, v19, v22, vcc
	v_sub_f32_e32 v22, 1.0, v14
.LBB0_1141:
	s_andn2_saveexec_b64 s[14:15], s[14:15]
	v_mul_f32_e32 v14, v21, v21
	v_fmamk_f32 v22, v14, 0xba1345e1, v3
	v_fmaak_f32 v22, v14, v22, 0xbcdac9b8
	v_fmaak_f32 v22, v14, v22, 0x3de703be
	v_fmaak_f32 v22, v14, v22, 0xbec09330
	v_fmaak_f32 v14, v14, v22, 0x3e0375d0
	v_fma_f32 v22, |v21|, v14, |v21|
	s_or_b64 exec, exec, s[14:15]
	v_ashrrev_i32_e32 v33, 31, v15
	v_mov_b32_e32 v32, v15
	v_lshl_add_u64 v[14:15], v[32:33], 2, s[8:9]
	v_mov_b32_e32 v31, v44
	v_add_co_u32_e32 v16, vcc, 0x10000, v16
	v_cvt_f32_f16_sdwa v24, v24 dst_sel:DWORD dst_unused:UNUSED_PAD src0_sel:WORD_1
	s_nop 0
	v_addc_co_u32_e32 v17, vcc, 0, v17, vcc
	v_mov_b32_e32 v16, v45
	v_cvt_f32_f16_sdwa v17, v30 dst_sel:DWORD dst_unused:UNUSED_PAD src0_sel:WORD_1
	v_cvt_f32_f16_sdwa v29, v29 dst_sel:DWORD dst_unused:UNUSED_PAD src0_sel:WORD_1
	v_cvt_f32_f16_sdwa v23, v23 dst_sel:DWORD dst_unused:UNUSED_PAD src0_sel:WORD_1
	v_cvt_f32_f16_sdwa v25, v25 dst_sel:DWORD dst_unused:UNUSED_PAD src0_sel:WORD_1
	v_add_f32_e32 v17, 0, v17
	v_add_f32_e32 v17, v17, v24
	v_add_f32_e32 v17, v17, v29
	v_add_f32_e32 v17, v17, v23
	v_cvt_f32_f16_sdwa v23, v26 dst_sel:DWORD dst_unused:UNUSED_PAD src0_sel:WORD_1
	v_cvt_f32_f16_sdwa v24, v28 dst_sel:DWORD dst_unused:UNUSED_PAD src0_sel:WORD_1
	v_cvt_f32_f16_sdwa v26, v27 dst_sel:DWORD dst_unused:UNUSED_PAD src0_sel:WORD_1
	v_add_f32_e32 v17, v17, v23
	v_add_f32_e32 v17, v17, v24
	v_add_f32_e32 v17, v17, v25
	v_add_f32_e32 v17, v17, v26
	s_waitcnt vmcnt(1)
	v_mul_f32_e32 v17, v17, v31
	v_mul_f32_e32 v23, 0x3f3504f3, v17
	v_cmp_nlt_f32_e64 s[14:15], |v23|, 1.0
	s_and_saveexec_b64 s[26:27], s[14:15]
	s_xor_b64 s[14:15], exec, s[26:27]
	s_cbranch_execz .LBB0_1145
	v_fma_f32 v24, |v23|, s2, v18
	v_fma_f32 v24, |v23|, v24, s16
	v_fma_f32 v24, |v23|, v24, s17
	v_fma_f32 v24, |v23|, v24, s18
	v_fma_f32 v24, |v23|, v24, s19
	v_fma_f32 v24, |v23|, v24, s20
	v_fma_f32 v24, |v23|, v24, |v23|
	v_mul_f32_e32 v25, 0xbfb8aa3b, v24
	v_fma_f32 v26, v24, s21, -v25
	v_rndne_f32_e32 v27, v25
	v_fmac_f32_e32 v26, 0xb2a5705f, v24
	v_sub_f32_e32 v25, v25, v27
	v_add_f32_e32 v25, v25, v26
	v_cvt_i32_f32_e32 v26, v27
	v_exp_f32_e32 v25, v25
	v_cmp_nlt_f32_e32 vcc, s22, v24
	v_ldexp_f32 v25, v25, v26
	s_nop 0
	v_cndmask_b32_e32 v25, 0, v25, vcc
	v_cmp_ngt_f32_e32 vcc, s23, v24
	s_nop 1
	v_cndmask_b32_e32 v24, v19, v25, vcc
	v_sub_f32_e32 v24, 1.0, v24

.LBB0_3037:
	s_or_b64 exec, exec, s[16:17]
	v_add_co_u32_e32 v14, vcc, 0x10000, v14
	v_bfi_b32 v21, s26, v22, v21
	s_nop 0
	v_addc_co_u32_e32 v15, vcc, 0, v15, vcc
	v_mov_b32_e32 v25, v46
	v_bfi_b32 v22, s26, v24, v23
	v_mul_f32_e32 v20, 0.5, v20
	v_mul_f32_e32 v17, 0.5, v17
	v_add_f32_e32 v21, 1.0, v21
	v_add_f32_e32 v22, 1.0, v22
	v_mul_f32_e32 v20, v20, v21
	v_mul_f32_e32 v17, v17, v22
	v_readlane_b32 s28, v250, 0
	v_add_u32_e32 v2, s76, v2
	v_mul_f32_e32 v12, v12, v20
	v_mul_f32_e32 v13, v13, v17
	v_readlane_b32 s30, v250, 2
	v_readlane_b32 s31, v250, 3
	v_cmp_lt_i32_e32 vcc, s27, v2
	s_waitcnt vmcnt(1)
	v_mul_f32_e32 v12, v16, v12
	v_lshl_add_u64 v[14:15], s[30:31], 0, v[6:7]
	v_lshl_add_u64 v[4:5], v[4:5], 0, s[12:13]
	v_lshl_add_u64 v[6:7], v[6:7], 0, s[12:13]
	v_lshl_add_u64 v[8:9], v[8:9], 0, s[14:15]
	s_or_b64 s[0:1], vcc, s[0:1]
	v_lshl_add_u64 v[10:11], v[10:11], 0, s[14:15]
	v_readlane_b32 s29, v250, 1
	s_waitcnt vmcnt(0)
	v_mul_f32_e32 v13, v25, v13
	v_cvt_pk_f16_f32 v12, v12, v13
	global_store_dword v[14:15], v12, off
	s_andn2_b64 exec, exec, s[0:1]
	s_cbranch_execz .LBB0_3046
.LBB0_3038:
	v_lshl_add_u64 v[12:13], s[30:31], 0, v[8:9]
	v_add_co_u32_e32 v12, vcc, 0x2ade6000, v12
	v_lshl_add_u64 v[16:17], s[30:31], 0, v[10:11]
	s_nop 0
	v_addc_co_u32_e32 v13, vcc, 0, v13, vcc
	global_load_dwordx2 v[14:15], v[12:13], off
	v_lshl_add_u64 v[12:13], s[30:31], 0, v[4:5]
	v_add_co_u32_e32 v20, vcc, 0x40d86000, v12
	s_nop 1
	v_addc_co_u32_e32 v21, vcc, 0, v13, vcc
	v_add_co_u32_e32 v22, vcc, 0x41206000, v12
	s_nop 1
	v_addc_co_u32_e32 v23, vcc, 0, v13, vcc
	v_add_co_u32_e32 v26, vcc, 0x41686000, v12
	s_nop 1
	v_addc_co_u32_e32 v27, vcc, 0, v13, vcc
	v_add_co_u32_e32 v28, vcc, 0x41b06000, v12
	s_nop 1
	v_addc_co_u32_e32 v29, vcc, 0, v13, vcc
	v_add_co_u32_e32 v32, vcc, 0x41f86000, v12
	global_load_dword v24, v[22:23], off
	s_nop 0
	global_load_dword v23, v[28:29], off
	v_addc_co_u32_e32 v33, vcc, 0, v13, vcc
	v_add_co_u32_e32 v34, vcc, 0x42406000, v12
	s_waitcnt vmcnt(0)
	v_cvt_f32_f16_e32 v31, v23
	v_addc_co_u32_e32 v35, vcc, 0, v13, vcc
	v_add_co_u32_e32 v36, vcc, 0x42886000, v12
	s_nop 1
	v_addc_co_u32_e32 v37, vcc, 0, v13, vcc
	global_load_dword v30, v[20:21], off
	global_load_dword v29, v[26:27], off
	s_nop 0
	global_load_dword v26, v[32:33], off
	global_load_dword v25, v[36:37], off
	v_add_co_u32_e32 v12, vcc, 0x42d06000, v12
	s_waitcnt vmcnt(2)
	v_cvt_f32_f16_e32 v22, v29
	v_addc_co_u32_e32 v13, vcc, 0, v13, vcc
	global_load_dword v28, v[34:35], off
	global_load_dword v27, v[12:13], off
	v_add_co_u32_e32 v20, vcc, 0x2b6e6000, v16
	v_ashrrev_i32_e32 v13, 31, v14
	s_nop 0
	v_addc_co_u32_e32 v21, vcc, 0, v17, vcc
	v_mov_b32_e32 v12, v14
	v_lshl_add_u64 v[16:17], v[12:13], 2, s[10:11]
	global_load_dwordx2 v[12:13], v[20:21], off
	global_load_dword v14, v[16:17], off
	s_mov_b64 s[98:99], 0x10000
	v_ashrrev_i32_e32 v41, 31, v15
	v_mov_b32_e32 v40, v15
	v_lshl_add_u64 v[40:41], v[40:41], 2, s[10:11]
	global_load_dword v44, v[40:41], off
	v_lshl_add_u64 v[42:43], v[16:17], 0, s[98:99]
	global_load_dword v45, v[42:43], off
	v_lshl_add_u64 v[42:43], v[40:41], 0, s[98:99]
	global_load_dword v46, v[42:43], off
	v_cvt_f32_f16_e32 v20, v30
	v_cvt_f32_f16_e32 v21, v24
	v_add_f32_e32 v20, 0, v20
	v_add_f32_e32 v20, v20, v21
	s_waitcnt vmcnt(5)
	v_cvt_f32_f16_e32 v21, v26
	v_add_f32_e32 v20, v20, v22
	v_add_f32_e32 v20, v20, v31
	s_waitcnt vmcnt(4)
	v_cvt_f32_f16_e32 v31, v25
	v_add_f32_e32 v20, v20, v21
	s_waitcnt vmcnt(3)
	v_cvt_f32_f16_e32 v22, v28
	s_waitcnt vmcnt(2)
	v_cvt_f32_f16_e32 v32, v27
	v_add_f32_e32 v20, v20, v22
	v_add_f32_e32 v20, v20, v31
	v_add_f32_e32 v20, v20, v32
	s_waitcnt vmcnt(0)
	v_mul_f32_e32 v20, v20, v14
	v_mul_f32_e32 v21, 0x3f3504f3, v20
	v_cmp_nlt_f32_e64 s[16:17], |v21|, 1.0
	s_and_saveexec_b64 s[28:29], s[16:17]
	s_xor_b64 s[16:17], exec, s[28:29]
	s_cbranch_execz .LBB0_3040
	v_fma_f32 v14, |v21|, s2, v18
	v_fma_f32 v14, |v21|, v14, s18
	v_fma_f32 v14, |v21|, v14, s19
	v_fma_f32 v14, |v21|, v14, s20
	v_fma_f32 v14, |v21|, v14, s21
	v_fma_f32 v14, |v21|, v14, s22
	v_fma_f32 v14, |v21|, v14, |v21|
	v_mul_f32_e32 v22, 0xbfb8aa3b, v14
	v_fma_f32 v31, v14, s23, -v22
	v_rndne_f32_e32 v32, v22
	v_fmac_f32_e32 v31, 0xb2a5705f, v14
	v_sub_f32_e32 v22, v22, v32
	v_add_f32_e32 v22, v22, v31
	v_cvt_i32_f32_e32 v31, v32
	v_exp_f32_e32 v22, v22
	v_cmp_nlt_f32_e32 vcc, s24, v14
	v_ldexp_f32 v22, v22, v31
	s_nop 0
	v_cndmask_b32_e32 v22, 0, v22, vcc
	v_cmp_ngt_f32_e32 vcc, s25, v14
	s_nop 1
	v_cndmask_b32_e32 v14, v19, v22, vcc
	v_sub_f32_e32 v22, 1.0, v14
.LBB0_3040:
	s_andn2_saveexec_b64 s[16:17], s[16:17]
	v_mul_f32_e32 v14, v21, v21
	v_fmamk_f32 v22, v14, 0xba1345e1, v3
	v_fmaak_f32 v22, v14, v22, 0xbcdac9b8
	v_fmaak_f32 v22, v14, v22, 0x3de703be
	v_fmaak_f32 v22, v14, v22, 0xbec09330
	v_fmaak_f32 v14, v14, v22, 0x3e0375d0
	v_fma_f32 v22, |v21|, v14, |v21|
	s_or_b64 exec, exec, s[16:17]
	v_ashrrev_i32_e32 v33, 31, v15
	v_mov_b32_e32 v32, v15
	v_lshl_add_u64 v[14:15], v[32:33], 2, s[10:11]
	v_mov_b32_e32 v31, v44
	v_add_co_u32_e32 v16, vcc, 0x10000, v16
	v_cvt_f32_f16_sdwa v24, v24 dst_sel:DWORD dst_unused:UNUSED_PAD src0_sel:WORD_1
	s_nop 0
	v_addc_co_u32_e32 v17, vcc, 0, v17, vcc
	v_mov_b32_e32 v16, v45
	v_cvt_f32_f16_sdwa v17, v30 dst_sel:DWORD dst_unused:UNUSED_PAD src0_sel:WORD_1
	v_cvt_f32_f16_sdwa v29, v29 dst_sel:DWORD dst_unused:UNUSED_PAD src0_sel:WORD_1
	v_cvt_f32_f16_sdwa v23, v23 dst_sel:DWORD dst_unused:UNUSED_PAD src0_sel:WORD_1
	v_cvt_f32_f16_sdwa v25, v25 dst_sel:DWORD dst_unused:UNUSED_PAD src0_sel:WORD_1
	v_add_f32_e32 v17, 0, v17
	v_add_f32_e32 v17, v17, v24
	v_add_f32_e32 v17, v17, v29
	v_add_f32_e32 v17, v17, v23
	v_cvt_f32_f16_sdwa v23, v26 dst_sel:DWORD dst_unused:UNUSED_PAD src0_sel:WORD_1
	v_cvt_f32_f16_sdwa v24, v28 dst_sel:DWORD dst_unused:UNUSED_PAD src0_sel:WORD_1
	v_cvt_f32_f16_sdwa v26, v27 dst_sel:DWORD dst_unused:UNUSED_PAD src0_sel:WORD_1
	v_add_f32_e32 v17, v17, v23
	v_add_f32_e32 v17, v17, v24
	v_add_f32_e32 v17, v17, v25
	v_add_f32_e32 v17, v17, v26
	s_waitcnt vmcnt(1)
	v_mul_f32_e32 v17, v17, v31
	v_mul_f32_e32 v23, 0x3f3504f3, v17
	v_cmp_nlt_f32_e64 s[16:17], |v23|, 1.0
	s_and_saveexec_b64 s[28:29], s[16:17]
	s_xor_b64 s[16:17], exec, s[28:29]
	s_cbranch_execz .LBB0_3044
	v_fma_f32 v24, |v23|, s2, v18
	v_fma_f32 v24, |v23|, v24, s18
	v_fma_f32 v24, |v23|, v24, s19
	v_fma_f32 v24, |v23|, v24, s20
	v_fma_f32 v24, |v23|, v24, s21
	v_fma_f32 v24, |v23|, v24, s22
	v_fma_f32 v24, |v23|, v24, |v23|
	v_mul_f32_e32 v25, 0xbfb8aa3b, v24
	v_fma_f32 v26, v24, s23, -v25
	v_rndne_f32_e32 v27, v25
	v_fmac_f32_e32 v26, 0xb2a5705f, v24
	v_sub_f32_e32 v25, v25, v27
	v_add_f32_e32 v25, v25, v26
	v_cvt_i32_f32_e32 v26, v27
	v_exp_f32_e32 v25, v25
	v_cmp_nlt_f32_e32 vcc, s24, v24
	v_ldexp_f32 v25, v25, v26
	s_nop 0
	v_cndmask_b32_e32 v25, 0, v25, vcc
	v_cmp_ngt_f32_e32 vcc, s25, v24
	s_nop 1
	v_cndmask_b32_e32 v24, v19, v25, vcc
	v_sub_f32_e32 v24, 1.0, v24

.LBB0_4022:
	s_or_b64 exec, exec, s[10:11]
	v_add_co_u32_e32 v14, vcc, 0x10000, v14
	v_bfi_b32 v21, s21, v22, v21
	s_nop 0
	v_addc_co_u32_e32 v15, vcc, 0, v15, vcc
	v_mov_b32_e32 v25, v46
	v_bfi_b32 v22, s21, v24, v23
	v_mul_f32_e32 v20, 0.5, v20
	v_mul_f32_e32 v17, 0.5, v17
	v_add_f32_e32 v21, 1.0, v21
	v_add_f32_e32 v22, 1.0, v22
	v_mul_f32_e32 v20, v20, v21
	v_mul_f32_e32 v17, v17, v22
	v_add_u32_e32 v2, s76, v2
	v_mul_f32_e32 v12, v12, v20
	v_mul_f32_e32 v13, v13, v17
	v_cmp_lt_i32_e32 vcc, s22, v2
	s_waitcnt vmcnt(1)
	v_mul_f32_e32 v12, v16, v12
	v_lshl_add_u64 v[14:15], s[54:55], 0, v[6:7]
	v_lshl_add_u64 v[4:5], v[4:5], 0, s[6:7]
	v_lshl_add_u64 v[6:7], v[6:7], 0, s[6:7]
	v_lshl_add_u64 v[8:9], v[8:9], 0, s[8:9]
	s_or_b64 s[0:1], vcc, s[0:1]
	v_lshl_add_u64 v[10:11], v[10:11], 0, s[8:9]
	s_waitcnt vmcnt(0)
	v_mul_f32_e32 v13, v25, v13
	v_cvt_pk_f16_f32 v12, v12, v13
	global_store_dword v[14:15], v12, off
	s_andn2_b64 exec, exec, s[0:1]
	s_cbranch_execz .LBB0_4031
.LBB0_4023:
	v_lshl_add_u64 v[12:13], s[54:55], 0, v[8:9]
	v_add_co_u32_e32 v12, vcc, 0x2ade6000, v12
	v_lshl_add_u64 v[16:17], s[54:55], 0, v[10:11]
	s_nop 0
	v_addc_co_u32_e32 v13, vcc, 0, v13, vcc
	global_load_dwordx2 v[14:15], v[12:13], off
	v_lshl_add_u64 v[12:13], s[54:55], 0, v[4:5]
	v_add_co_u32_e32 v20, vcc, 0x40d86000, v12
	s_nop 1
	v_addc_co_u32_e32 v21, vcc, 0, v13, vcc
	v_add_co_u32_e32 v26, vcc, 0x41206000, v12
	s_nop 1
	v_addc_co_u32_e32 v27, vcc, 0, v13, vcc
	v_add_co_u32_e32 v30, vcc, 0x41686000, v12
	s_nop 1
	v_addc_co_u32_e32 v31, vcc, 0, v13, vcc
	v_add_co_u32_e32 v28, vcc, 0x41b06000, v12
	s_nop 1
	v_addc_co_u32_e32 v29, vcc, 0, v13, vcc
	v_add_co_u32_e32 v32, vcc, 0x41f86000, v12
	global_load_dword v24, v[26:27], off
	global_load_dword v23, v[28:29], off
	v_addc_co_u32_e32 v33, vcc, 0, v13, vcc
	v_add_co_u32_e32 v34, vcc, 0x42406000, v12
	s_nop 1
	v_addc_co_u32_e32 v35, vcc, 0, v13, vcc
	v_add_co_u32_e32 v36, vcc, 0x42886000, v12
	s_nop 1
	v_addc_co_u32_e32 v37, vcc, 0, v13, vcc
	global_load_dword v28, v[20:21], off
	global_load_dword v27, v[30:31], off
	global_load_dword v26, v[32:33], off
	global_load_dword v25, v[36:37], off
	v_add_co_u32_e32 v12, vcc, 0x42d06000, v12
	s_waitcnt vmcnt(4)
	v_cvt_f32_f16_e32 v31, v23
	v_addc_co_u32_e32 v13, vcc, 0, v13, vcc
	global_load_dword v30, v[34:35], off
	global_load_dword v29, v[12:13], off
	v_add_co_u32_e32 v20, vcc, 0x2b6e6000, v16
	v_ashrrev_i32_e32 v13, 31, v14
	s_nop 0
	v_addc_co_u32_e32 v21, vcc, 0, v17, vcc
	v_mov_b32_e32 v12, v14
	v_lshl_add_u64 v[16:17], v[12:13], 2, s[4:5]
	global_load_dwordx2 v[12:13], v[20:21], off
	global_load_dword v14, v[16:17], off
	s_mov_b64 s[98:99], 0x10000
	v_ashrrev_i32_e32 v41, 31, v15
	v_mov_b32_e32 v40, v15
	v_lshl_add_u64 v[40:41], v[40:41], 2, s[4:5]
	global_load_dword v44, v[40:41], off
	v_lshl_add_u64 v[42:43], v[16:17], 0, s[98:99]
	global_load_dword v45, v[42:43], off
	v_lshl_add_u64 v[42:43], v[40:41], 0, s[98:99]
	global_load_dword v46, v[42:43], off
	s_waitcnt vmcnt(7)
	v_cvt_f32_f16_e32 v20, v28
	v_cvt_f32_f16_e32 v21, v24
	s_waitcnt vmcnt(6)
	v_cvt_f32_f16_e32 v22, v27
	v_add_f32_e32 v20, 0, v20
	v_add_f32_e32 v20, v20, v21
	s_waitcnt vmcnt(5)
	v_cvt_f32_f16_e32 v21, v26
	v_add_f32_e32 v20, v20, v22
	v_add_f32_e32 v20, v20, v31
	s_waitcnt vmcnt(4)
	v_cvt_f32_f16_e32 v31, v25
	v_add_f32_e32 v20, v20, v21
	s_waitcnt vmcnt(3)
	v_cvt_f32_f16_e32 v22, v30
	s_waitcnt vmcnt(2)
	v_cvt_f32_f16_e32 v32, v29
	v_add_f32_e32 v20, v20, v22
	v_add_f32_e32 v20, v20, v31
	v_add_f32_e32 v20, v20, v32
	s_waitcnt vmcnt(0)
	v_mul_f32_e32 v20, v20, v14
	v_mul_f32_e32 v21, 0x3f3504f3, v20
	v_cmp_nlt_f32_e64 s[10:11], |v21|, 1.0
	s_and_saveexec_b64 s[24:25], s[10:11]
	s_xor_b64 s[10:11], exec, s[24:25]
	s_cbranch_execz .LBB0_4025
	v_fma_f32 v14, |v21|, s12, v18
	v_fma_f32 v14, |v21|, v14, s13
	v_fma_f32 v14, |v21|, v14, s14
	v_fma_f32 v14, |v21|, v14, s15
	v_fma_f32 v14, |v21|, v14, s16
	v_fma_f32 v14, |v21|, v14, s17
	v_fma_f32 v14, |v21|, v14, |v21|
	v_mul_f32_e32 v22, 0xbfb8aa3b, v14
	v_fma_f32 v31, v14, s18, -v22
	v_rndne_f32_e32 v32, v22
	v_fmac_f32_e32 v31, 0xb2a5705f, v14
	v_sub_f32_e32 v22, v22, v32
	v_add_f32_e32 v22, v22, v31
	v_cvt_i32_f32_e32 v31, v32
	v_exp_f32_e32 v22, v22
	v_cmp_nlt_f32_e32 vcc, s19, v14
	v_ldexp_f32 v22, v22, v31
	s_nop 0
	v_cndmask_b32_e32 v22, 0, v22, vcc
	v_cmp_ngt_f32_e32 vcc, s20, v14
	s_nop 1
	v_cndmask_b32_e32 v14, v19, v22, vcc
	v_sub_f32_e32 v22, 1.0, v14
.LBB0_4025:
	s_andn2_saveexec_b64 s[10:11], s[10:11]
	v_mul_f32_e32 v14, v21, v21
	v_fmamk_f32 v22, v14, 0xba1345e1, v3
	v_fmaak_f32 v22, v14, v22, 0xbcdac9b8
	v_fmaak_f32 v22, v14, v22, 0x3de703be
	v_fmaak_f32 v22, v14, v22, 0xbec09330
	v_fmaak_f32 v14, v14, v22, 0x3e0375d0
	v_fma_f32 v22, |v21|, v14, |v21|
	s_or_b64 exec, exec, s[10:11]
	v_ashrrev_i32_e32 v33, 31, v15
	v_mov_b32_e32 v32, v15
	v_lshl_add_u64 v[14:15], v[32:33], 2, s[4:5]
	v_mov_b32_e32 v31, v44
	v_add_co_u32_e32 v16, vcc, 0x10000, v16
	v_cvt_f32_f16_sdwa v24, v24 dst_sel:DWORD dst_unused:UNUSED_PAD src0_sel:WORD_1
	s_nop 0
	v_addc_co_u32_e32 v17, vcc, 0, v17, vcc
	v_mov_b32_e32 v16, v45
	v_cvt_f32_f16_sdwa v17, v28 dst_sel:DWORD dst_unused:UNUSED_PAD src0_sel:WORD_1
	v_cvt_f32_f16_sdwa v27, v27 dst_sel:DWORD dst_unused:UNUSED_PAD src0_sel:WORD_1
	v_cvt_f32_f16_sdwa v23, v23 dst_sel:DWORD dst_unused:UNUSED_PAD src0_sel:WORD_1
	v_cvt_f32_f16_sdwa v25, v25 dst_sel:DWORD dst_unused:UNUSED_PAD src0_sel:WORD_1
	v_add_f32_e32 v17, 0, v17
	v_add_f32_e32 v17, v17, v24
	v_add_f32_e32 v17, v17, v27
	v_add_f32_e32 v17, v17, v23
	v_cvt_f32_f16_sdwa v23, v26 dst_sel:DWORD dst_unused:UNUSED_PAD src0_sel:WORD_1
	v_cvt_f32_f16_sdwa v24, v30 dst_sel:DWORD dst_unused:UNUSED_PAD src0_sel:WORD_1
	v_cvt_f32_f16_sdwa v26, v29 dst_sel:DWORD dst_unused:UNUSED_PAD src0_sel:WORD_1
	v_add_f32_e32 v17, v17, v23
	v_add_f32_e32 v17, v17, v24
	v_add_f32_e32 v17, v17, v25
	v_add_f32_e32 v17, v17, v26
	s_waitcnt vmcnt(1)
	v_mul_f32_e32 v17, v17, v31
	v_mul_f32_e32 v23, 0x3f3504f3, v17
	v_cmp_nlt_f32_e64 s[10:11], |v23|, 1.0
	s_and_saveexec_b64 s[24:25], s[10:11]
	s_xor_b64 s[10:11], exec, s[24:25]
	s_cbranch_execz .LBB0_4029
	v_fma_f32 v24, |v23|, s12, v18
	v_fma_f32 v24, |v23|, v24, s13
	v_fma_f32 v24, |v23|, v24, s14
	v_fma_f32 v24, |v23|, v24, s15
	v_fma_f32 v24, |v23|, v24, s16
	v_fma_f32 v24, |v23|, v24, s17
	v_fma_f32 v24, |v23|, v24, |v23|
	v_mul_f32_e32 v25, 0xbfb8aa3b, v24
	v_fma_f32 v26, v24, s18, -v25
	v_rndne_f32_e32 v27, v25
	v_fmac_f32_e32 v26, 0xb2a5705f, v24
	v_sub_f32_e32 v25, v25, v27
	v_add_f32_e32 v25, v25, v26
	v_cvt_i32_f32_e32 v26, v27
	v_exp_f32_e32 v25, v25
	v_cmp_nlt_f32_e32 vcc, s19, v24
	v_ldexp_f32 v25, v25, v26
	s_nop 0
	v_cndmask_b32_e32 v25, 0, v25, vcc
	v_cmp_ngt_f32_e32 vcc, s20, v24
	s_nop 1
	v_cndmask_b32_e32 v24, v19, v25, vcc
	v_sub_f32_e32 v24, 1.0, v24
